# grid seams: per-CU L1 invalidate issued at arrival (before polling / alongside the leader's L2 write-back) instead of after the release; only sc1 polling loads run in between
# speedup vs baseline: 1.0282x; 1.0100x over previous
; __device__ __forceinline__ unsigned xb_ld(unsigned* p)              { return __hip_atomic_load(p, __ATOMIC_RELAXED, __HIP_MEMORY_SCOPE_AGENT); }
; __device__ __forceinline__ unsigned xb_add(unsigned* p, unsigned v) { return __hip_atomic_fetch_add(p, v, __ATOMIC_RELAXED, __HIP_MEMORY_SCOPE_AGENT); }
; #define XB_SPIN(cond, bar) do { unsigned _sp = 0; while (cond) { __builtin_amdgcn_s_sleep(1); \
;     if ((++_sp & 255u) == 0u) { if (xb_ld(&(bar)[XB_TMO])) break; if (_sp > XB_SPIN_CAP) { atomicAdd(&(bar)[XB_TMO], 1u); break; } } } } while (0)
; __device__ __forceinline__ void xcd_barrier(const XcdBarrier& b) {
;     ...
;         unsigned nloc = b.st[0], nx = b.st[1];
;         if (nloc == 0u) { xcd_barrier_complete(bar, b.x, nloc, nx); b.st[0] = nloc; b.st[1] = nx; }
;         const unsigned old = xb_add(&bar[XB_XSUB(b.x)], 1u);
;         const unsigned gen = old / nloc;
;         if (old + 1u == (gen + 1u) * nloc) {
;             __builtin_amdgcn_fence(__ATOMIC_RELEASE, "agent");
;             asm volatile("s_waitcnt vmcnt(0)" ::: "memory");
;             const unsigned og = xb_add(&bar[XB_TOP], 1u);
;             const unsigned tg = og / nx;
;             if (og + 1u == (tg + 1u) * nx) xb_add(&bar[XB_TOPGEN], 1u);
;             else XB_SPIN(xb_ld(&bar[XB_TOPGEN]) == tg, bar);
;             __builtin_amdgcn_fence(__ATOMIC_ACQUIRE, "agent");
;             xb_add(&bar[XB_XGEN(b.x)], 1u);
;             asm volatile("s_waitcnt vmcnt(0)" ::: "memory");
;         } else {
;             XB_SPIN(xb_ld(&bar[XB_XGEN(b.x)]) == gen, bar);
.LBB0_207:
	s_or_b64 exec, exec, s[14:15]
	v_cvt_f32_u32_e32 v5, v3
	s_waitcnt vmcnt(0)
	v_readfirstlane_b32 s0, v4
	v_sub_u32_e32 v4, 0, v3
	v_rcp_iflag_f32_e32 v5, v5
	v_add_u32_e32 v6, s0, v2
	v_mul_f32_e32 v5, 0x4f7ffffe, v5
	v_cvt_u32_f32_e32 v5, v5
	v_mul_lo_u32 v2, v4, v5
	v_mul_hi_u32 v2, v5, v2
	v_add_u32_e32 v2, v5, v2
	v_mul_hi_u32 v2, v6, v2
	v_mul_lo_u32 v4, v2, v3
	v_sub_u32_e32 v4, v6, v4
	v_add_u32_e32 v5, 1, v2
	v_cmp_ge_u32_e32 vcc, v4, v3
	s_nop 1
	v_cndmask_b32_e32 v2, v2, v5, vcc
	v_sub_u32_e32 v5, v4, v3
	v_cndmask_b32_e32 v4, v4, v5, vcc
	v_add_u32_e32 v5, 1, v2
	v_cmp_ge_u32_e32 vcc, v4, v3
	v_add_u32_e32 v4, 1, v6
	s_nop 0
	v_cndmask_b32_e32 v2, v2, v5, vcc
	v_mul_lo_u32 v5, v3, v2
	v_add_u32_e32 v3, v5, v3
	v_cmp_ne_u32_e32 vcc, v4, v3
	s_and_saveexec_b64 s[0:1], vcc
	s_xor_b64 s[12:13], exec, s[0:1]
	s_cbranch_execz .LBB0_221
	s_waitcnt lgkmcnt(0)
	buffer_inv sc1
	v_mov_b32_e32 v1, 0x2000
	global_load_dword v1, v1, s[10:11] offset:1024 sc1
	s_add_u32 s18, s10, 0x2400
	s_addc_u32 s19, s11, 0
	s_waitcnt vmcnt(0)
	v_cmp_eq_u32_e32 vcc, v1, v2
	s_and_saveexec_b64 s[14:15], vcc
	s_cbranch_execz .LBB0_220
	s_add_u32 s16, s26, 0xff00200
	s_addc_u32 s17, s27, 0
	s_mov_b32 s0, 1
	s_mov_b64 s[20:21], 0
	v_mov_b32_e32 v1, 0
	s_branch .LBB0_211

; __device__ __forceinline__ unsigned xb_ld(unsigned* p)              { return __hip_atomic_load(p, __ATOMIC_RELAXED, __HIP_MEMORY_SCOPE_AGENT); }
; __device__ __forceinline__ unsigned xb_add(unsigned* p, unsigned v) { return __hip_atomic_fetch_add(p, v, __ATOMIC_RELAXED, __HIP_MEMORY_SCOPE_AGENT); }
; #define XB_SPIN(cond, bar) do { unsigned _sp = 0; while (cond) { __builtin_amdgcn_s_sleep(1); \
;     if ((++_sp & 255u) == 0u) { if (xb_ld(&(bar)[XB_TMO])) break; if (_sp > XB_SPIN_CAP) { atomicAdd(&(bar)[XB_TMO], 1u); break; } } } } while (0)
; __device__ __forceinline__ void xcd_barrier(const XcdBarrier& b) {
;     ...
;         const unsigned old = xb_add(&bar[XB_XSUB(b.x)], 1u);
;         const unsigned gen = old / nloc;
;         if (old + 1u == (gen + 1u) * nloc) {
;             __builtin_amdgcn_fence(__ATOMIC_RELEASE, "agent");
;             asm volatile("s_waitcnt vmcnt(0)" ::: "memory");
;             const unsigned og = xb_add(&bar[XB_TOP], 1u);
;             const unsigned tg = og / nx;
;             if (og + 1u == (tg + 1u) * nx) xb_add(&bar[XB_TOPGEN], 1u);
;             else XB_SPIN(xb_ld(&bar[XB_TOPGEN]) == tg, bar);
;             __builtin_amdgcn_fence(__ATOMIC_ACQUIRE, "agent");
;             xb_add(&bar[XB_XGEN(b.x)], 1u);
;             asm volatile("s_waitcnt vmcnt(0)" ::: "memory");
;         } else {
;             XB_SPIN(xb_ld(&bar[XB_XGEN(b.x)]) == gen, bar);
;             __builtin_amdgcn_fence(__ATOMIC_ACQUIRE, "agent");
;             asm volatile("s_waitcnt vmcnt(0)" ::: "memory");
.LBB0_220:
	s_or_b64 exec, exec, s[14:15]
	s_waitcnt vmcnt(0) lgkmcnt(0)
	s_waitcnt vmcnt(0)
.LBB0_221:
	s_andn2_saveexec_b64 s[0:1], s[12:13]
	s_cbranch_execz .LBB0_241
	s_mov_b64 s[12:13], exec
	buffer_inv sc1
	buffer_wbl2 sc1
	s_waitcnt lgkmcnt(0)
	s_waitcnt vmcnt(0)
	v_mbcnt_lo_u32_b32 v2, s12, 0
	v_mbcnt_hi_u32_b32 v2, s13, v2
	v_cmp_eq_u32_e32 vcc, 0, v2
	s_and_saveexec_b64 s[14:15], vcc
	s_cbranch_execz .LBB0_224
	s_bcnt1_i32_b64 s0, s[12:13]
	v_mov_b32_e32 v3, 0xff03000
	v_mov_b32_e32 v4, s0
	global_atomic_add v3, v3, v4, s[26:27] offset:1024 sc0

; __device__ __forceinline__ unsigned xb_ld(unsigned* p)              { return __hip_atomic_load(p, __ATOMIC_RELAXED, __HIP_MEMORY_SCOPE_AGENT); }
; __device__ __forceinline__ unsigned xb_add(unsigned* p, unsigned v) { return __hip_atomic_fetch_add(p, v, __ATOMIC_RELAXED, __HIP_MEMORY_SCOPE_AGENT); }
; #define XB_SPIN(cond, bar) do { unsigned _sp = 0; while (cond) { __builtin_amdgcn_s_sleep(1); \
;     if ((++_sp & 255u) == 0u) { if (xb_ld(&(bar)[XB_TMO])) break; if (_sp > XB_SPIN_CAP) { atomicAdd(&(bar)[XB_TMO], 1u); break; } } } } while (0)
; __device__ __forceinline__ void xcd_barrier(const XcdBarrier& b) {
;     ...
;             const unsigned og = xb_add(&bar[XB_TOP], 1u);
;             const unsigned tg = og / nx;
;             if (og + 1u == (tg + 1u) * nx) xb_add(&bar[XB_TOPGEN], 1u);
;             else XB_SPIN(xb_ld(&bar[XB_TOPGEN]) == tg, bar);
;             __builtin_amdgcn_fence(__ATOMIC_ACQUIRE, "agent");
;             xb_add(&bar[XB_XGEN(b.x)], 1u);
;             asm volatile("s_waitcnt vmcnt(0)" ::: "memory");
.LBB0_238:
	s_or_b64 exec, exec, s[12:13]
	s_mov_b64 s[12:13], exec
	v_mbcnt_lo_u32_b32 v1, s12, 0
	v_mbcnt_hi_u32_b32 v1, s13, v1
	v_cmp_eq_u32_e32 vcc, 0, v1
	s_waitcnt vmcnt(0) lgkmcnt(0)
	s_and_saveexec_b64 s[14:15], vcc
	s_cbranch_execz .LBB0_240
	s_bcnt1_i32_b64 s0, s[12:13]
	v_mov_b32_e32 v1, 0x2000
	v_mov_b32_e32 v2, s0
	global_atomic_add v1, v2, s[10:11] offset:1024

; __device__ __forceinline__ unsigned xb_ld(unsigned* p)              { return __hip_atomic_load(p, __ATOMIC_RELAXED, __HIP_MEMORY_SCOPE_AGENT); }
; #define XB_SPIN(cond, bar) do { unsigned _sp = 0; while (cond) { __builtin_amdgcn_s_sleep(1); \
;     if ((++_sp & 255u) == 0u) { if (xb_ld(&(bar)[XB_TMO])) break; if (_sp > XB_SPIN_CAP) { atomicAdd(&(bar)[XB_TMO], 1u); break; } } } } while (0)
; __device__ __forceinline__ void xcd_barrier(const XcdBarrier& b) {
;     ...
;             XB_SPIN(xb_ld(&bar[XB_XGEN(b.x)]) == gen, bar);
;             __builtin_amdgcn_fence(__ATOMIC_ACQUIRE, "agent");
;             asm volatile("s_waitcnt vmcnt(0)" ::: "memory");
.LBB0_447:
	s_or_b64 exec, exec, s[14:15]
	s_waitcnt vmcnt(0)
	s_waitcnt vmcnt(0)

; __device__ __forceinline__ unsigned xb_ld(unsigned* p)              { return __hip_atomic_load(p, __ATOMIC_RELAXED, __HIP_MEMORY_SCOPE_AGENT); }
; __device__ __forceinline__ unsigned xb_add(unsigned* p, unsigned v) { return __hip_atomic_fetch_add(p, v, __ATOMIC_RELAXED, __HIP_MEMORY_SCOPE_AGENT); }
; #define XB_SPIN(cond, bar) do { unsigned _sp = 0; while (cond) { __builtin_amdgcn_s_sleep(1); \
;     if ((++_sp & 255u) == 0u) { if (xb_ld(&(bar)[XB_TMO])) break; if (_sp > XB_SPIN_CAP) { atomicAdd(&(bar)[XB_TMO], 1u); break; } } } } while (0)
; __device__ __forceinline__ void xcd_barrier(const XcdBarrier& b) {
;     ...
;             const unsigned og = xb_add(&bar[XB_TOP], 1u);
;             const unsigned tg = og / nx;
;             if (og + 1u == (tg + 1u) * nx) xb_add(&bar[XB_TOPGEN], 1u);
;             else XB_SPIN(xb_ld(&bar[XB_TOPGEN]) == tg, bar);
;             __builtin_amdgcn_fence(__ATOMIC_ACQUIRE, "agent");
;             xb_add(&bar[XB_XGEN(b.x)], 1u);
.LBB0_465:
	s_or_b64 exec, exec, s[12:13]
	s_mov_b64 s[12:13], exec
	v_mbcnt_lo_u32_b32 v1, s12, 0
	v_mbcnt_hi_u32_b32 v1, s13, v1
	v_cmp_eq_u32_e32 vcc, 0, v1
	s_waitcnt vmcnt(0)
	s_and_saveexec_b64 s[14:15], vcc
	s_cbranch_execz .LBB0_467
	s_bcnt1_i32_b64 s0, s[12:13]
	v_mov_b32_e32 v1, 0x2000
	v_mov_b32_e32 v2, s0
	global_atomic_add v1, v2, s[10:11] offset:1024

; __device__ __forceinline__ unsigned xb_ld(unsigned* p)              { return __hip_atomic_load(p, __ATOMIC_RELAXED, __HIP_MEMORY_SCOPE_AGENT); }
; __device__ __forceinline__ unsigned xb_add(unsigned* p, unsigned v) { return __hip_atomic_fetch_add(p, v, __ATOMIC_RELAXED, __HIP_MEMORY_SCOPE_AGENT); }
; #define XB_SPIN(cond, bar) do { unsigned _sp = 0; while (cond) { __builtin_amdgcn_s_sleep(1); \
;     if ((++_sp & 255u) == 0u) { if (xb_ld(&(bar)[XB_TMO])) break; if (_sp > XB_SPIN_CAP) { atomicAdd(&(bar)[XB_TMO], 1u); break; } } } } while (0)
; __device__ __forceinline__ void xcd_barrier(const XcdBarrier& b) {
;     ...
;         unsigned nloc = b.st[0], nx = b.st[1];
;         if (nloc == 0u) { xcd_barrier_complete(bar, b.x, nloc, nx); b.st[0] = nloc; b.st[1] = nx; }
;         const unsigned old = xb_add(&bar[XB_XSUB(b.x)], 1u);
;         const unsigned gen = old / nloc;
;         if (old + 1u == (gen + 1u) * nloc) {
;             __builtin_amdgcn_fence(__ATOMIC_RELEASE, "agent");
;             asm volatile("s_waitcnt vmcnt(0)" ::: "memory");
;             const unsigned og = xb_add(&bar[XB_TOP], 1u);
;             const unsigned tg = og / nx;
;             if (og + 1u == (tg + 1u) * nx) xb_add(&bar[XB_TOPGEN], 1u);
;             else XB_SPIN(xb_ld(&bar[XB_TOPGEN]) == tg, bar);
;             __builtin_amdgcn_fence(__ATOMIC_ACQUIRE, "agent");
;             xb_add(&bar[XB_XGEN(b.x)], 1u);
;             asm volatile("s_waitcnt vmcnt(0)" ::: "memory");
;         } else {
;             XB_SPIN(xb_ld(&bar[XB_XGEN(b.x)]) == gen, bar);
.LBB0_1317:
	s_or_b64 exec, exec, s[12:13]
	v_cvt_f32_u32_e32 v5, v3
	s_waitcnt vmcnt(0)
	v_readfirstlane_b32 s2, v4
	v_sub_u32_e32 v4, 0, v3
	v_rcp_iflag_f32_e32 v5, v5
	v_add_u32_e32 v6, s2, v2
	v_mul_f32_e32 v5, 0x4f7ffffe, v5
	v_cvt_u32_f32_e32 v5, v5
	v_mul_lo_u32 v2, v4, v5
	v_mul_hi_u32 v2, v5, v2
	v_add_u32_e32 v2, v5, v2
	v_mul_hi_u32 v2, v6, v2
	v_mul_lo_u32 v4, v2, v3
	v_sub_u32_e32 v4, v6, v4
	v_add_u32_e32 v5, 1, v2
	v_cmp_ge_u32_e32 vcc, v4, v3
	s_nop 1
	v_cndmask_b32_e32 v2, v2, v5, vcc
	v_sub_u32_e32 v5, v4, v3
	v_cndmask_b32_e32 v4, v4, v5, vcc
	v_add_u32_e32 v5, 1, v2
	v_cmp_ge_u32_e32 vcc, v4, v3
	v_add_u32_e32 v4, 1, v6
	s_nop 0
	v_cndmask_b32_e32 v2, v2, v5, vcc
	v_mul_lo_u32 v5, v3, v2
	v_add_u32_e32 v3, v5, v3
	v_cmp_ne_u32_e32 vcc, v4, v3
	s_and_saveexec_b64 s[2:3], vcc
	s_xor_b64 s[10:11], exec, s[2:3]
	s_cbranch_execz .LBB0_1331
	s_waitcnt lgkmcnt(0)
	buffer_inv sc1
	v_mov_b32_e32 v1, 0x2000
	global_load_dword v1, v1, s[8:9] offset:1024 sc1
	s_add_u32 s44, s8, 0x2400
	s_addc_u32 s45, s9, 0
	s_waitcnt vmcnt(0)
	v_cmp_eq_u32_e32 vcc, v1, v2
	s_and_saveexec_b64 s[12:13], vcc
	s_cbranch_execz .LBB0_1330
	s_add_u32 s42, s26, 0xff00200
	s_addc_u32 s43, s27, 0
	s_mov_b32 s2, 1
	s_mov_b64 s[46:47], 0
	v_mov_b32_e32 v1, 0
	s_branch .LBB0_1321

; __device__ __forceinline__ unsigned xb_ld(unsigned* p)              { return __hip_atomic_load(p, __ATOMIC_RELAXED, __HIP_MEMORY_SCOPE_AGENT); }
; __device__ __forceinline__ unsigned xb_add(unsigned* p, unsigned v) { return __hip_atomic_fetch_add(p, v, __ATOMIC_RELAXED, __HIP_MEMORY_SCOPE_AGENT); }
; #define XB_SPIN(cond, bar) do { unsigned _sp = 0; while (cond) { __builtin_amdgcn_s_sleep(1); \
;     if ((++_sp & 255u) == 0u) { if (xb_ld(&(bar)[XB_TMO])) break; if (_sp > XB_SPIN_CAP) { atomicAdd(&(bar)[XB_TMO], 1u); break; } } } } while (0)
; __device__ __forceinline__ void xcd_barrier(const XcdBarrier& b) {
;     ...
;         const unsigned old = xb_add(&bar[XB_XSUB(b.x)], 1u);
;         const unsigned gen = old / nloc;
;         if (old + 1u == (gen + 1u) * nloc) {
;             __builtin_amdgcn_fence(__ATOMIC_RELEASE, "agent");
;             asm volatile("s_waitcnt vmcnt(0)" ::: "memory");
;             const unsigned og = xb_add(&bar[XB_TOP], 1u);
;             const unsigned tg = og / nx;
;             if (og + 1u == (tg + 1u) * nx) xb_add(&bar[XB_TOPGEN], 1u);
;             else XB_SPIN(xb_ld(&bar[XB_TOPGEN]) == tg, bar);
;             __builtin_amdgcn_fence(__ATOMIC_ACQUIRE, "agent");
;             xb_add(&bar[XB_XGEN(b.x)], 1u);
;             asm volatile("s_waitcnt vmcnt(0)" ::: "memory");
;         } else {
;             XB_SPIN(xb_ld(&bar[XB_XGEN(b.x)]) == gen, bar);
;             __builtin_amdgcn_fence(__ATOMIC_ACQUIRE, "agent");
;             asm volatile("s_waitcnt vmcnt(0)" ::: "memory");
.LBB0_1330:
	s_or_b64 exec, exec, s[12:13]
	s_waitcnt vmcnt(0)
	s_waitcnt vmcnt(0)
.LBB0_1331:
	s_andn2_saveexec_b64 s[2:3], s[10:11]
	s_cbranch_execz .LBB0_1351
	s_mov_b64 s[10:11], exec
	buffer_inv sc1
	buffer_wbl2 sc1
	s_waitcnt lgkmcnt(0)
	s_waitcnt vmcnt(0)
	v_mbcnt_lo_u32_b32 v2, s10, 0
	v_mbcnt_hi_u32_b32 v2, s11, v2
	v_cmp_eq_u32_e32 vcc, 0, v2
	s_and_saveexec_b64 s[12:13], vcc
	s_cbranch_execz .LBB0_1334
	s_bcnt1_i32_b64 s2, s[10:11]
	v_mov_b32_e32 v3, 0xff03000
	v_mov_b32_e32 v4, s2
	global_atomic_add v3, v3, v4, s[26:27] offset:1024 sc0

; __device__ __forceinline__ unsigned xb_ld(unsigned* p)              { return __hip_atomic_load(p, __ATOMIC_RELAXED, __HIP_MEMORY_SCOPE_AGENT); }
; __device__ __forceinline__ unsigned xb_add(unsigned* p, unsigned v) { return __hip_atomic_fetch_add(p, v, __ATOMIC_RELAXED, __HIP_MEMORY_SCOPE_AGENT); }
; #define XB_SPIN(cond, bar) do { unsigned _sp = 0; while (cond) { __builtin_amdgcn_s_sleep(1); \
;     if ((++_sp & 255u) == 0u) { if (xb_ld(&(bar)[XB_TMO])) break; if (_sp > XB_SPIN_CAP) { atomicAdd(&(bar)[XB_TMO], 1u); break; } } } } while (0)
; __device__ __forceinline__ void xcd_barrier(const XcdBarrier& b) {
;     ...
;             const unsigned og = xb_add(&bar[XB_TOP], 1u);
;             const unsigned tg = og / nx;
;             if (og + 1u == (tg + 1u) * nx) xb_add(&bar[XB_TOPGEN], 1u);
;             else XB_SPIN(xb_ld(&bar[XB_TOPGEN]) == tg, bar);
;             __builtin_amdgcn_fence(__ATOMIC_ACQUIRE, "agent");
;             xb_add(&bar[XB_XGEN(b.x)], 1u);
;             asm volatile("s_waitcnt vmcnt(0)" ::: "memory");
.LBB0_1348:
	s_or_b64 exec, exec, s[10:11]
	s_mov_b64 s[10:11], exec
	v_mbcnt_lo_u32_b32 v1, s10, 0
	v_mbcnt_hi_u32_b32 v1, s11, v1
	v_cmp_eq_u32_e32 vcc, 0, v1
	s_waitcnt vmcnt(0)
	s_and_saveexec_b64 s[12:13], vcc
	s_cbranch_execz .LBB0_1350
	s_bcnt1_i32_b64 s2, s[10:11]
	v_mov_b32_e32 v1, 0x2000
	v_mov_b32_e32 v2, s2
	global_atomic_add v1, v2, s[8:9] offset:1024

; __device__ __forceinline__ unsigned xb_ld(unsigned* p)              { return __hip_atomic_load(p, __ATOMIC_RELAXED, __HIP_MEMORY_SCOPE_AGENT); }
; __device__ __forceinline__ unsigned xb_add(unsigned* p, unsigned v) { return __hip_atomic_fetch_add(p, v, __ATOMIC_RELAXED, __HIP_MEMORY_SCOPE_AGENT); }
; #define XB_SPIN(cond, bar) do { unsigned _sp = 0; while (cond) { __builtin_amdgcn_s_sleep(1); \
;     if ((++_sp & 255u) == 0u) { if (xb_ld(&(bar)[XB_TMO])) break; if (_sp > XB_SPIN_CAP) { atomicAdd(&(bar)[XB_TMO], 1u); break; } } } } while (0)
; __device__ __forceinline__ void xcd_barrier(const XcdBarrier& b) {
;     ...
;         unsigned nloc = b.st[0], nx = b.st[1];
;         if (nloc == 0u) { xcd_barrier_complete(bar, b.x, nloc, nx); b.st[0] = nloc; b.st[1] = nx; }
;         const unsigned old = xb_add(&bar[XB_XSUB(b.x)], 1u);
;         const unsigned gen = old / nloc;
;         if (old + 1u == (gen + 1u) * nloc) {
;             __builtin_amdgcn_fence(__ATOMIC_RELEASE, "agent");
;             asm volatile("s_waitcnt vmcnt(0)" ::: "memory");
;             const unsigned og = xb_add(&bar[XB_TOP], 1u);
;             const unsigned tg = og / nx;
;             if (og + 1u == (tg + 1u) * nx) xb_add(&bar[XB_TOPGEN], 1u);
;             else XB_SPIN(xb_ld(&bar[XB_TOPGEN]) == tg, bar);
;             __builtin_amdgcn_fence(__ATOMIC_ACQUIRE, "agent");
;             xb_add(&bar[XB_XGEN(b.x)], 1u);
;             asm volatile("s_waitcnt vmcnt(0)" ::: "memory");
;         } else {
;             XB_SPIN(xb_ld(&bar[XB_XGEN(b.x)]) == gen, bar);
.LBB0_1552:
	s_or_b64 exec, exec, s[12:13]
	v_cvt_f32_u32_e32 v5, v3
	s_waitcnt vmcnt(0)
	v_readfirstlane_b32 s2, v4
	v_sub_u32_e32 v4, 0, v3
	v_rcp_iflag_f32_e32 v5, v5
	v_add_u32_e32 v6, s2, v2
	v_mul_f32_e32 v5, 0x4f7ffffe, v5
	v_cvt_u32_f32_e32 v5, v5
	v_mul_lo_u32 v2, v4, v5
	v_mul_hi_u32 v2, v5, v2
	v_add_u32_e32 v2, v5, v2
	v_mul_hi_u32 v2, v6, v2
	v_mul_lo_u32 v4, v2, v3
	v_sub_u32_e32 v4, v6, v4
	v_add_u32_e32 v5, 1, v2
	v_cmp_ge_u32_e32 vcc, v4, v3
	s_nop 1
	v_cndmask_b32_e32 v2, v2, v5, vcc
	v_sub_u32_e32 v5, v4, v3
	v_cndmask_b32_e32 v4, v4, v5, vcc
	v_add_u32_e32 v5, 1, v2
	v_cmp_ge_u32_e32 vcc, v4, v3
	v_add_u32_e32 v4, 1, v6
	s_nop 0
	v_cndmask_b32_e32 v2, v2, v5, vcc
	v_mul_lo_u32 v5, v3, v2
	v_add_u32_e32 v3, v5, v3
	v_cmp_ne_u32_e32 vcc, v4, v3
	s_and_saveexec_b64 s[2:3], vcc
	s_xor_b64 s[10:11], exec, s[2:3]
	s_cbranch_execz .LBB0_1566
	s_waitcnt lgkmcnt(0)
	buffer_inv sc1
	v_mov_b32_e32 v1, 0x2000
	global_load_dword v1, v1, s[8:9] offset:1024 sc1
	s_add_u32 s16, s8, 0x2400
	s_addc_u32 s17, s9, 0
	s_waitcnt vmcnt(0)
	v_cmp_eq_u32_e32 vcc, v1, v2
	s_and_saveexec_b64 s[12:13], vcc
	s_cbranch_execz .LBB0_1565
	s_add_u32 s14, s26, 0xff00200
	s_addc_u32 s15, s27, 0
	s_mov_b32 s2, 1
	s_mov_b64 s[18:19], 0
	v_mov_b32_e32 v1, 0
	s_branch .LBB0_1556

; __device__ __forceinline__ unsigned xb_ld(unsigned* p)              { return __hip_atomic_load(p, __ATOMIC_RELAXED, __HIP_MEMORY_SCOPE_AGENT); }
; __device__ __forceinline__ unsigned xb_add(unsigned* p, unsigned v) { return __hip_atomic_fetch_add(p, v, __ATOMIC_RELAXED, __HIP_MEMORY_SCOPE_AGENT); }
; #define XB_SPIN(cond, bar) do { unsigned _sp = 0; while (cond) { __builtin_amdgcn_s_sleep(1); \
;     if ((++_sp & 255u) == 0u) { if (xb_ld(&(bar)[XB_TMO])) break; if (_sp > XB_SPIN_CAP) { atomicAdd(&(bar)[XB_TMO], 1u); break; } } } } while (0)
; __device__ __forceinline__ void xcd_barrier(const XcdBarrier& b) {
;     ...
;         unsigned nloc = b.st[0], nx = b.st[1];
;         if (nloc == 0u) { xcd_barrier_complete(bar, b.x, nloc, nx); b.st[0] = nloc; b.st[1] = nx; }
;         const unsigned old = xb_add(&bar[XB_XSUB(b.x)], 1u);
;         const unsigned gen = old / nloc;
;         if (old + 1u == (gen + 1u) * nloc) {
;             __builtin_amdgcn_fence(__ATOMIC_RELEASE, "agent");
;             asm volatile("s_waitcnt vmcnt(0)" ::: "memory");
;             const unsigned og = xb_add(&bar[XB_TOP], 1u);
;             const unsigned tg = og / nx;
;             if (og + 1u == (tg + 1u) * nx) xb_add(&bar[XB_TOPGEN], 1u);
;             else XB_SPIN(xb_ld(&bar[XB_TOPGEN]) == tg, bar);
;             __builtin_amdgcn_fence(__ATOMIC_ACQUIRE, "agent");
;             xb_add(&bar[XB_XGEN(b.x)], 1u);
;             asm volatile("s_waitcnt vmcnt(0)" ::: "memory");
;         } else {
;             XB_SPIN(xb_ld(&bar[XB_XGEN(b.x)]) == gen, bar);
.LBB0_1814:
	s_or_b64 exec, exec, s[10:11]
	v_cvt_f32_u32_e32 v4, v2
	s_waitcnt vmcnt(0)
	v_readfirstlane_b32 s2, v3
	v_sub_u32_e32 v3, 0, v2
	v_rcp_iflag_f32_e32 v4, v4
	v_add_u32_e32 v5, s2, v1
	v_mul_f32_e32 v4, 0x4f7ffffe, v4
	v_cvt_u32_f32_e32 v4, v4
	v_mul_lo_u32 v1, v3, v4
	v_mul_hi_u32 v1, v4, v1
	v_add_u32_e32 v1, v4, v1
	v_mul_hi_u32 v1, v5, v1
	v_mul_lo_u32 v3, v1, v2
	v_sub_u32_e32 v3, v5, v3
	v_add_u32_e32 v4, 1, v1
	v_cmp_ge_u32_e32 vcc, v3, v2
	s_nop 1
	v_cndmask_b32_e32 v1, v1, v4, vcc
	v_sub_u32_e32 v4, v3, v2
	v_cndmask_b32_e32 v3, v3, v4, vcc
	v_add_u32_e32 v4, 1, v1
	v_cmp_ge_u32_e32 vcc, v3, v2
	v_add_u32_e32 v3, 1, v5
	s_nop 0
	v_cndmask_b32_e32 v1, v1, v4, vcc
	v_mul_lo_u32 v4, v2, v1
	v_add_u32_e32 v2, v4, v2
	v_cmp_ne_u32_e32 vcc, v3, v2
	s_and_saveexec_b64 s[2:3], vcc
	s_xor_b64 s[8:9], exec, s[2:3]
	s_cbranch_execz .LBB0_1828
	s_waitcnt lgkmcnt(0)
	buffer_inv sc1
	v_mov_b32_e32 v0, 0x2000
	global_load_dword v0, v0, s[6:7] offset:1024 sc1
	s_add_u32 s16, s6, 0x2400
	s_addc_u32 s17, s7, 0
	s_waitcnt vmcnt(0)
	v_cmp_eq_u32_e32 vcc, v0, v1
	s_and_saveexec_b64 s[10:11], vcc
	s_cbranch_execz .LBB0_1827
	s_add_u32 s14, s26, 0xff00200
	s_addc_u32 s15, s27, 0
	s_mov_b32 s2, 1
	s_mov_b64 s[18:19], 0
	v_mov_b32_e32 v0, 0
	s_branch .LBB0_1818

; __device__ __forceinline__ unsigned xb_ld(unsigned* p)              { return __hip_atomic_load(p, __ATOMIC_RELAXED, __HIP_MEMORY_SCOPE_AGENT); }
; __device__ __forceinline__ unsigned xb_add(unsigned* p, unsigned v) { return __hip_atomic_fetch_add(p, v, __ATOMIC_RELAXED, __HIP_MEMORY_SCOPE_AGENT); }
; #define XB_SPIN(cond, bar) do { unsigned _sp = 0; while (cond) { __builtin_amdgcn_s_sleep(1); \
;     if ((++_sp & 255u) == 0u) { if (xb_ld(&(bar)[XB_TMO])) break; if (_sp > XB_SPIN_CAP) { atomicAdd(&(bar)[XB_TMO], 1u); break; } } } } while (0)
; __device__ __forceinline__ void xcd_barrier(const XcdBarrier& b) {
;     ...
;         const unsigned old = xb_add(&bar[XB_XSUB(b.x)], 1u);
;         const unsigned gen = old / nloc;
;         if (old + 1u == (gen + 1u) * nloc) {
;             __builtin_amdgcn_fence(__ATOMIC_RELEASE, "agent");
;             asm volatile("s_waitcnt vmcnt(0)" ::: "memory");
;             const unsigned og = xb_add(&bar[XB_TOP], 1u);
;             const unsigned tg = og / nx;
;             if (og + 1u == (tg + 1u) * nx) xb_add(&bar[XB_TOPGEN], 1u);
;             else XB_SPIN(xb_ld(&bar[XB_TOPGEN]) == tg, bar);
;             __builtin_amdgcn_fence(__ATOMIC_ACQUIRE, "agent");
;             xb_add(&bar[XB_XGEN(b.x)], 1u);
;             asm volatile("s_waitcnt vmcnt(0)" ::: "memory");
;         } else {
;             XB_SPIN(xb_ld(&bar[XB_XGEN(b.x)]) == gen, bar);
;             __builtin_amdgcn_fence(__ATOMIC_ACQUIRE, "agent");
;             asm volatile("s_waitcnt vmcnt(0)" ::: "memory");
.LBB0_1827:
	s_or_b64 exec, exec, s[10:11]
	s_waitcnt vmcnt(0)
	s_waitcnt vmcnt(0)
.LBB0_1828:
	s_andn2_saveexec_b64 s[2:3], s[8:9]
	s_cbranch_execz .LBB0_1848
	s_mov_b64 s[8:9], exec
	buffer_inv sc1
	buffer_wbl2 sc1
	s_waitcnt lgkmcnt(0)
	s_waitcnt vmcnt(0)
	v_mbcnt_lo_u32_b32 v1, s8, 0
	v_mbcnt_hi_u32_b32 v1, s9, v1
	v_cmp_eq_u32_e32 vcc, 0, v1
	s_and_saveexec_b64 s[10:11], vcc
	s_cbranch_execz .LBB0_1831
	s_bcnt1_i32_b64 s2, s[8:9]
	v_mov_b32_e32 v2, 0xff03000
	v_mov_b32_e32 v3, s2
	global_atomic_add v2, v2, v3, s[26:27] offset:1024 sc0

; __device__ __forceinline__ unsigned xb_ld(unsigned* p)              { return __hip_atomic_load(p, __ATOMIC_RELAXED, __HIP_MEMORY_SCOPE_AGENT); }
; __device__ __forceinline__ unsigned xb_add(unsigned* p, unsigned v) { return __hip_atomic_fetch_add(p, v, __ATOMIC_RELAXED, __HIP_MEMORY_SCOPE_AGENT); }
; #define XB_SPIN(cond, bar) do { unsigned _sp = 0; while (cond) { __builtin_amdgcn_s_sleep(1); \
;     if ((++_sp & 255u) == 0u) { if (xb_ld(&(bar)[XB_TMO])) break; if (_sp > XB_SPIN_CAP) { atomicAdd(&(bar)[XB_TMO], 1u); break; } } } } while (0)
; __device__ __forceinline__ void xcd_barrier(const XcdBarrier& b) {
;     ...
;             const unsigned og = xb_add(&bar[XB_TOP], 1u);
;             const unsigned tg = og / nx;
;             if (og + 1u == (tg + 1u) * nx) xb_add(&bar[XB_TOPGEN], 1u);
;             else XB_SPIN(xb_ld(&bar[XB_TOPGEN]) == tg, bar);
;             __builtin_amdgcn_fence(__ATOMIC_ACQUIRE, "agent");
;             xb_add(&bar[XB_XGEN(b.x)], 1u);
;             asm volatile("s_waitcnt vmcnt(0)" ::: "memory");
.LBB0_1845:
	s_or_b64 exec, exec, s[8:9]
	s_mov_b64 s[8:9], exec
	v_mbcnt_lo_u32_b32 v0, s8, 0
	v_mbcnt_hi_u32_b32 v0, s9, v0
	v_cmp_eq_u32_e32 vcc, 0, v0
	s_waitcnt vmcnt(0)
	s_and_saveexec_b64 s[10:11], vcc
	s_cbranch_execz .LBB0_1847
	s_bcnt1_i32_b64 s2, s[8:9]
	v_mov_b32_e32 v0, 0x2000
	v_mov_b32_e32 v1, s2
	global_atomic_add v0, v1, s[6:7] offset:1024
